# v29 + attention QK block (both main-loop copies): K-fragment ds_reads software-pipelined 6-7 deep using dead P-block registers, MFMA order unchanged
# speedup vs baseline: 1.0041x; 1.0026x over previous
.LBB0_1734:
	v_add3_u32 v181, s16, v174, v144
	ds_read_b128 v[182:185], v181
	ds_read_b128 v[64:67], v181 offset:8704
	ds_read_b128 v[186:189], v181 offset:32
	ds_read_b128 v[190:193], v181 offset:8736
	ds_read_b128 v[196:199], v181 offset:64
	ds_read_b128 v[200:203], v181 offset:8768
	ds_read_b128 v[204:207], v181 offset:96
	s_andn2_b64 vcc, exec, s[8:9]
	s_waitcnt lgkmcnt(6)
	v_mfma_f32_32x32x16_bf16 v[80:95], v[182:185], v[112:115], 0
	ds_read_b128 v[182:185], v181 offset:8800
	s_waitcnt lgkmcnt(6)
	v_mfma_f32_32x32x16_bf16 v[64:79], v[64:67], v[112:115], 0
	s_waitcnt lgkmcnt(5)
	v_mfma_f32_32x32x16_bf16 v[80:95], v[186:189], v[116:119], v[80:95]
	ds_read_b128 v[186:189], v181 offset:128
	s_waitcnt lgkmcnt(5)
	v_mfma_f32_32x32x16_bf16 v[64:79], v[190:193], v[116:119], v[64:79]
	ds_read_b128 v[190:193], v181 offset:8832
	s_waitcnt lgkmcnt(5)
	v_mfma_f32_32x32x16_bf16 v[80:95], v[196:199], v[120:123], v[80:95]
	ds_read_b128 v[196:199], v181 offset:160
	s_waitcnt lgkmcnt(5)
	v_mfma_f32_32x32x16_bf16 v[64:79], v[200:203], v[120:123], v[64:79]
	ds_read_b128 v[200:203], v181 offset:8864
	s_waitcnt lgkmcnt(5)
	v_mfma_f32_32x32x16_bf16 v[80:95], v[204:207], v[124:127], v[80:95]
	ds_read_b128 v[204:207], v181 offset:192
	s_waitcnt lgkmcnt(5)
	v_mfma_f32_32x32x16_bf16 v[64:79], v[182:185], v[124:127], v[64:79]
	ds_read_b128 v[182:185], v181 offset:8896
	s_waitcnt lgkmcnt(5)
	v_mfma_f32_32x32x16_bf16 v[80:95], v[186:189], v[128:131], v[80:95]
	ds_read_b128 v[186:189], v181 offset:224
	s_waitcnt lgkmcnt(5)
	v_mfma_f32_32x32x16_bf16 v[64:79], v[190:193], v[128:131], v[64:79]
	ds_read_b128 v[190:193], v181 offset:8928
	s_waitcnt lgkmcnt(5)
	v_mfma_f32_32x32x16_bf16 v[80:95], v[196:199], v[132:135], v[80:95]
	s_waitcnt lgkmcnt(4)
	v_mfma_f32_32x32x16_bf16 v[64:79], v[200:203], v[132:135], v[64:79]
	s_waitcnt lgkmcnt(3)
	v_mfma_f32_32x32x16_bf16 v[80:95], v[204:207], v[136:139], v[80:95]
	s_waitcnt lgkmcnt(2)
	v_mfma_f32_32x32x16_bf16 v[64:79], v[182:185], v[136:139], v[64:79]
	s_waitcnt lgkmcnt(1)
	v_mfma_f32_32x32x16_bf16 v[80:95], v[186:189], v[140:143], v[80:95]
	s_waitcnt lgkmcnt(0)
	v_mfma_f32_32x32x16_bf16 v[64:79], v[190:193], v[140:143], v[64:79]
	s_cbranch_vccnz .LBB0_1738
	s_lshl_b32 s16, s17, 6
	s_or_b32 s10, s16, 63
	v_cmp_gt_i32_e32 vcc, s10, v172
	s_and_saveexec_b64 s[10:11], vcc
	s_cbranch_execz .LBB0_1737
	v_or_b32_e32 v181, s16, v147
	v_cmp_le_i32_e32 vcc, v181, v146
	v_or_b32_e32 v182, 32, v181
	s_nop 0
	v_cndmask_b32_e32 v80, v159, v80, vcc
	v_cmp_le_i32_e32 vcc, v182, v146
	v_or_b32_e32 v182, 33, v181
	s_nop 0
	v_cndmask_b32_e32 v64, v159, v64, vcc
	v_cmp_lt_i32_e32 vcc, v181, v146
	s_nop 1
	v_cndmask_b32_e32 v81, v159, v81, vcc
	v_cmp_le_i32_e32 vcc, v182, v146
	v_or_b32_e32 v182, 2, v181
	s_nop 0
	v_cndmask_b32_e32 v65, v159, v65, vcc
	v_cmp_le_i32_e32 vcc, v182, v146
	v_or_b32_e32 v182, 34, v181
	s_nop 0
	v_cndmask_b32_e32 v82, v159, v82, vcc
	v_cmp_le_i32_e32 vcc, v182, v146
	v_or_b32_e32 v182, 3, v181
	s_nop 0
	v_cndmask_b32_e32 v66, v159, v66, vcc
	v_cmp_le_i32_e32 vcc, v182, v146
	v_or_b32_e32 v182, 35, v181
	s_nop 0
	v_cndmask_b32_e32 v83, v159, v83, vcc
	v_cmp_le_i32_e32 vcc, v182, v146
	v_or_b32_e32 v182, 8, v181
	s_nop 0
	v_cndmask_b32_e32 v67, v159, v67, vcc
	v_cmp_le_i32_e32 vcc, v182, v146
	v_or_b32_e32 v182, 40, v181
	s_nop 0
	v_cndmask_b32_e32 v84, v159, v84, vcc
	v_cmp_le_i32_e32 vcc, v182, v146
	v_or_b32_e32 v182, 9, v181
	s_nop 0
	v_cndmask_b32_e32 v68, v159, v68, vcc
	v_cmp_le_i32_e32 vcc, v182, v146
	v_or_b32_e32 v182, 41, v181
	s_nop 0
	v_cndmask_b32_e32 v85, v159, v85, vcc
	v_cmp_le_i32_e32 vcc, v182, v146
	v_or_b32_e32 v182, 10, v181
	s_nop 0
	v_cndmask_b32_e32 v69, v159, v69, vcc
	v_cmp_le_i32_e32 vcc, v182, v146
	v_or_b32_e32 v182, 42, v181
	s_nop 0
	v_cndmask_b32_e32 v86, v159, v86, vcc
	v_cmp_le_i32_e32 vcc, v182, v146
	v_or_b32_e32 v182, 11, v181
	s_nop 0
	v_cndmask_b32_e32 v70, v159, v70, vcc
	v_cmp_le_i32_e32 vcc, v182, v146
	v_or_b32_e32 v182, 43, v181
	s_nop 0
	v_cndmask_b32_e32 v87, v159, v87, vcc
	v_cmp_le_i32_e32 vcc, v182, v146
	v_or_b32_e32 v182, 16, v181
	s_nop 0
	v_cndmask_b32_e32 v71, v159, v71, vcc
	v_cmp_le_i32_e32 vcc, v182, v146
	v_or_b32_e32 v182, 48, v181
	s_nop 0
	v_cndmask_b32_e32 v88, v159, v88, vcc
	v_cmp_le_i32_e32 vcc, v182, v146
	v_or_b32_e32 v182, 17, v181
	s_nop 0
	v_cndmask_b32_e32 v72, v159, v72, vcc
	v_cmp_le_i32_e32 vcc, v182, v146
	v_or_b32_e32 v182, 49, v181
	s_nop 0
	v_cndmask_b32_e32 v89, v159, v89, vcc
	v_cmp_le_i32_e32 vcc, v182, v146
	v_or_b32_e32 v182, 18, v181
	s_nop 0
	v_cndmask_b32_e32 v73, v159, v73, vcc
	v_cmp_le_i32_e32 vcc, v182, v146
	v_or_b32_e32 v182, 50, v181
	s_nop 0
	v_cndmask_b32_e32 v90, v159, v90, vcc
	v_cmp_le_i32_e32 vcc, v182, v146
	v_or_b32_e32 v182, 19, v181
	s_nop 0
	v_cndmask_b32_e32 v74, v159, v74, vcc
	v_cmp_le_i32_e32 vcc, v182, v146
	v_or_b32_e32 v182, 51, v181
	s_nop 0
	v_cndmask_b32_e32 v91, v159, v91, vcc
	v_cmp_le_i32_e32 vcc, v182, v146
	v_or_b32_e32 v182, 24, v181
	s_nop 0
	v_cndmask_b32_e32 v75, v159, v75, vcc
	v_cmp_le_i32_e32 vcc, v182, v146
	v_or_b32_e32 v182, 56, v181
	s_nop 0
	v_cndmask_b32_e32 v92, v159, v92, vcc
	v_cmp_le_i32_e32 vcc, v182, v146
	v_or_b32_e32 v182, 25, v181
	s_nop 0
	v_cndmask_b32_e32 v76, v159, v76, vcc
	v_cmp_le_i32_e32 vcc, v182, v146
	v_or_b32_e32 v182, 57, v181
	s_nop 0
	v_cndmask_b32_e32 v93, v159, v93, vcc
	v_cmp_le_i32_e32 vcc, v182, v146
	v_or_b32_e32 v182, 26, v181
	s_nop 0
	v_cndmask_b32_e32 v77, v159, v77, vcc
	v_cmp_le_i32_e32 vcc, v182, v146
	v_or_b32_e32 v182, 58, v181
	s_nop 0
	v_cndmask_b32_e32 v94, v159, v94, vcc
	v_cmp_le_i32_e32 vcc, v182, v146
	v_or_b32_e32 v182, 27, v181
	v_or_b32_e32 v181, 59, v181
	v_cndmask_b32_e32 v78, v159, v78, vcc
	v_cmp_le_i32_e32 vcc, v182, v146
	s_nop 1
	v_cndmask_b32_e32 v95, v159, v95, vcc
	v_cmp_le_i32_e32 vcc, v181, v146
	s_nop 1
	v_cndmask_b32_e32 v79, v159, v79, vcc

.LBB0_1777:
	v_add3_u32 v181, s17, v174, v144
	ds_read_b128 v[182:185], v181
	ds_read_b128 v[64:67], v181 offset:8704
	ds_read_b128 v[186:189], v181 offset:32
	ds_read_b128 v[190:193], v181 offset:8736
	ds_read_b128 v[196:199], v181 offset:64
	ds_read_b128 v[200:203], v181 offset:8768
	ds_read_b128 v[204:207], v181 offset:96
	s_andn2_b64 vcc, exec, s[8:9]
	s_waitcnt lgkmcnt(6)
	v_mfma_f32_32x32x16_bf16 v[80:95], v[182:185], v[112:115], 0
	ds_read_b128 v[182:185], v181 offset:8800
	s_waitcnt lgkmcnt(6)
	v_mfma_f32_32x32x16_bf16 v[64:79], v[64:67], v[112:115], 0
	s_waitcnt lgkmcnt(5)
	v_mfma_f32_32x32x16_bf16 v[80:95], v[186:189], v[116:119], v[80:95]
	ds_read_b128 v[186:189], v181 offset:128
	s_waitcnt lgkmcnt(5)
	v_mfma_f32_32x32x16_bf16 v[64:79], v[190:193], v[116:119], v[64:79]
	ds_read_b128 v[190:193], v181 offset:8832
	s_waitcnt lgkmcnt(5)
	v_mfma_f32_32x32x16_bf16 v[80:95], v[196:199], v[120:123], v[80:95]
	ds_read_b128 v[196:199], v181 offset:160
	s_waitcnt lgkmcnt(5)
	v_mfma_f32_32x32x16_bf16 v[64:79], v[200:203], v[120:123], v[64:79]
	ds_read_b128 v[200:203], v181 offset:8864
	s_waitcnt lgkmcnt(5)
	v_mfma_f32_32x32x16_bf16 v[80:95], v[204:207], v[124:127], v[80:95]
	ds_read_b128 v[204:207], v181 offset:192
	s_waitcnt lgkmcnt(5)
	v_mfma_f32_32x32x16_bf16 v[64:79], v[182:185], v[124:127], v[64:79]
	ds_read_b128 v[182:185], v181 offset:8896
	s_waitcnt lgkmcnt(5)
	v_mfma_f32_32x32x16_bf16 v[80:95], v[186:189], v[128:131], v[80:95]
	ds_read_b128 v[186:189], v181 offset:224
	s_waitcnt lgkmcnt(5)
	v_mfma_f32_32x32x16_bf16 v[64:79], v[190:193], v[128:131], v[64:79]
	ds_read_b128 v[190:193], v181 offset:8928
	s_waitcnt lgkmcnt(5)
	v_mfma_f32_32x32x16_bf16 v[80:95], v[196:199], v[132:135], v[80:95]
	s_waitcnt lgkmcnt(4)
	v_mfma_f32_32x32x16_bf16 v[64:79], v[200:203], v[132:135], v[64:79]
	s_waitcnt lgkmcnt(3)
	v_mfma_f32_32x32x16_bf16 v[80:95], v[204:207], v[136:139], v[80:95]
	s_waitcnt lgkmcnt(2)
	v_mfma_f32_32x32x16_bf16 v[64:79], v[182:185], v[136:139], v[64:79]
	s_waitcnt lgkmcnt(1)
	v_mfma_f32_32x32x16_bf16 v[80:95], v[186:189], v[140:143], v[80:95]
	s_waitcnt lgkmcnt(0)
	v_mfma_f32_32x32x16_bf16 v[64:79], v[190:193], v[140:143], v[64:79]
	s_cbranch_vccnz .LBB0_1781
	s_lshl_b32 s17, s18, 6
	s_or_b32 s10, s17, 63
	v_cmp_gt_i32_e32 vcc, s10, v173
	s_and_saveexec_b64 s[10:11], vcc
	s_cbranch_execz .LBB0_1780
	v_or_b32_e32 v181, s17, v147
	v_cmp_le_i32_e32 vcc, v181, v146
	v_or_b32_e32 v182, 32, v181
	s_nop 0
	v_cndmask_b32_e32 v80, v159, v80, vcc
	v_cmp_le_i32_e32 vcc, v182, v146
	v_or_b32_e32 v182, 33, v181
	s_nop 0
	v_cndmask_b32_e32 v64, v159, v64, vcc
	v_cmp_lt_i32_e32 vcc, v181, v146
	s_nop 1
	v_cndmask_b32_e32 v81, v159, v81, vcc
	v_cmp_le_i32_e32 vcc, v182, v146
	v_or_b32_e32 v182, 2, v181
	s_nop 0
	v_cndmask_b32_e32 v65, v159, v65, vcc
	v_cmp_le_i32_e32 vcc, v182, v146
	v_or_b32_e32 v182, 34, v181
	s_nop 0
	v_cndmask_b32_e32 v82, v159, v82, vcc
	v_cmp_le_i32_e32 vcc, v182, v146
	v_or_b32_e32 v182, 3, v181
	s_nop 0
	v_cndmask_b32_e32 v66, v159, v66, vcc
	v_cmp_le_i32_e32 vcc, v182, v146
	v_or_b32_e32 v182, 35, v181
	s_nop 0
	v_cndmask_b32_e32 v83, v159, v83, vcc
	v_cmp_le_i32_e32 vcc, v182, v146
	v_or_b32_e32 v182, 8, v181
	s_nop 0
	v_cndmask_b32_e32 v67, v159, v67, vcc
	v_cmp_le_i32_e32 vcc, v182, v146
	v_or_b32_e32 v182, 40, v181
	s_nop 0
	v_cndmask_b32_e32 v84, v159, v84, vcc
	v_cmp_le_i32_e32 vcc, v182, v146
	v_or_b32_e32 v182, 9, v181
	s_nop 0
	v_cndmask_b32_e32 v68, v159, v68, vcc
	v_cmp_le_i32_e32 vcc, v182, v146
	v_or_b32_e32 v182, 41, v181
	s_nop 0
	v_cndmask_b32_e32 v85, v159, v85, vcc
	v_cmp_le_i32_e32 vcc, v182, v146
	v_or_b32_e32 v182, 10, v181
	s_nop 0
	v_cndmask_b32_e32 v69, v159, v69, vcc
	v_cmp_le_i32_e32 vcc, v182, v146
	v_or_b32_e32 v182, 42, v181
	s_nop 0
	v_cndmask_b32_e32 v86, v159, v86, vcc
	v_cmp_le_i32_e32 vcc, v182, v146
	v_or_b32_e32 v182, 11, v181
	s_nop 0
	v_cndmask_b32_e32 v70, v159, v70, vcc
	v_cmp_le_i32_e32 vcc, v182, v146
	v_or_b32_e32 v182, 43, v181
	s_nop 0
	v_cndmask_b32_e32 v87, v159, v87, vcc
	v_cmp_le_i32_e32 vcc, v182, v146
	v_or_b32_e32 v182, 16, v181
	s_nop 0
	v_cndmask_b32_e32 v71, v159, v71, vcc
	v_cmp_le_i32_e32 vcc, v182, v146
	v_or_b32_e32 v182, 48, v181
	s_nop 0
	v_cndmask_b32_e32 v88, v159, v88, vcc
	v_cmp_le_i32_e32 vcc, v182, v146
	v_or_b32_e32 v182, 17, v181
	s_nop 0
	v_cndmask_b32_e32 v72, v159, v72, vcc
	v_cmp_le_i32_e32 vcc, v182, v146
	v_or_b32_e32 v182, 49, v181
	s_nop 0
	v_cndmask_b32_e32 v89, v159, v89, vcc
	v_cmp_le_i32_e32 vcc, v182, v146
	v_or_b32_e32 v182, 18, v181
	s_nop 0
	v_cndmask_b32_e32 v73, v159, v73, vcc
	v_cmp_le_i32_e32 vcc, v182, v146
	v_or_b32_e32 v182, 50, v181
	s_nop 0
	v_cndmask_b32_e32 v90, v159, v90, vcc
	v_cmp_le_i32_e32 vcc, v182, v146
	v_or_b32_e32 v182, 19, v181
	s_nop 0
	v_cndmask_b32_e32 v74, v159, v74, vcc
	v_cmp_le_i32_e32 vcc, v182, v146
	v_or_b32_e32 v182, 51, v181
	s_nop 0
	v_cndmask_b32_e32 v91, v159, v91, vcc
	v_cmp_le_i32_e32 vcc, v182, v146
	v_or_b32_e32 v182, 24, v181
	s_nop 0
	v_cndmask_b32_e32 v75, v159, v75, vcc
	v_cmp_le_i32_e32 vcc, v182, v146
	v_or_b32_e32 v182, 56, v181
	s_nop 0
	v_cndmask_b32_e32 v92, v159, v92, vcc
	v_cmp_le_i32_e32 vcc, v182, v146
	v_or_b32_e32 v182, 25, v181
	s_nop 0
	v_cndmask_b32_e32 v76, v159, v76, vcc
	v_cmp_le_i32_e32 vcc, v182, v146
	v_or_b32_e32 v182, 57, v181
	s_nop 0
	v_cndmask_b32_e32 v93, v159, v93, vcc
	v_cmp_le_i32_e32 vcc, v182, v146
	v_or_b32_e32 v182, 26, v181
	s_nop 0
	v_cndmask_b32_e32 v77, v159, v77, vcc
	v_cmp_le_i32_e32 vcc, v182, v146
	v_or_b32_e32 v182, 58, v181
	s_nop 0
	v_cndmask_b32_e32 v94, v159, v94, vcc
	v_cmp_le_i32_e32 vcc, v182, v146
	v_or_b32_e32 v182, 27, v181
	v_or_b32_e32 v181, 59, v181
	v_cndmask_b32_e32 v78, v159, v78, vcc
	v_cmp_le_i32_e32 vcc, v182, v146
	s_nop 1
	v_cndmask_b32_e32 v95, v159, v95, vcc
	v_cmp_le_i32_e32 vcc, v181, v146
	s_nop 1
	v_cndmask_b32_e32 v79, v159, v79, vcc
